# v20 + branch-projection phase of groups 1,2: idle workgroups 128..255 run 256 units (column tiles 6..13) of the next group's input projection; the following phase enumerates the remaining 640 units
# speedup vs baseline: 1.0199x; 1.0128x over previous
; #define KARG const __attribute__((address_space(4))) Params* Pp = (const __attribute__((address_space(4))) Params*)__builtin_amdgcn_kernarg_segment_ptr(); asm volatile("" : "+s"(Pp)); PARAMS P = *Pp;
; DI void prologue(PARAMS P, LAS unsigned char* lds, int wave, int lane) {
;     ...
;     for (int row = gw; row < MTOT; row += NGW) {
;         int g = 0, lr = row; if (row >= G0ROWS) { g = 1 + (row - G0ROWS) / GROWS; lr = (row - G0ROWS) % GROWS; }
;         const float* src = nullptr;
;         if (g != 0 || lr < 8192) src = P.in[0] + ((size_t)(4 * g + (lr >> 11)) * 2048 + (lr & 2047)) * D;
;         else if (lr < 8704) src = P.in[1] + (size_t)(lr - 8192) * D;
;         else if (lr < 8720) src = P.in[8] + (size_t)(lr - 8704) * D;
;         f32x4* dst = (f32x4*)(X + (size_t)row * D);
; #pragma unroll
;         for (int j = 0; j < 4; ++j) dst[lane + 64 * j] = src ? ((const f32x4*)src)[lane + 64 * j] : (f32x4){0.f, 0.f, 0.f, 0.f};
; __global__ void __launch_bounds__(NTHREADS, 2) fwd_kernel(Params P_) {
;     ...
;     const int hi = P_.hi < NPHASE ? P_.hi : NPHASE;
;     int ph0 = P_.lo;
;     if (ph0 == 0) {
;         { KARG if (PHMASK & 1) run_phase<0>(P, 0, 0); }
;         ph0 = 1;
;         if (ph0 < hi) grid.sync();
;     }
;     for (int ph = ph0; ph < hi; ++ph) {
.LBB0_84:
.LBB0_85:
	s_waitcnt vmcnt(0)
	v_mov_b32_e32 v6, 0
	v_mov_b32_e32 v7, v6
	v_mov_b32_e32 v8, v6
	v_mov_b32_e32 v9, v6
	global_store_dwordx4 v[10:11], v[2:5], off
	s_branch .LBB0_69
.Lend_near:
	s_endpgm
.LBB0_86:
	s_min_i32 s83, s15, 52
	s_cmp_lt_i32 s83, 2
	s_cbranch_scc1 .Lend_near
	s_mov_b32 s14, 0
	s_mov_b32 s101, 1

; #define TIDV tid_opaque()
; #define BIDX bid_opaque()
; #define GDIM gdim_opaque()
; template <int KIND> DI void run_phase(PARAMS P, int l, int g) {
;     ...
;     else if constexpr (KIND == 7) {
;         { pg8::Gemm gm{(const bf16_t*)((unsigned char*)P.out + DS_MIXB), wl + WL_WOUT, gr, D, D}; pg8::StaticOrder S; S.init(gr, D, GDIM, (BIDX + GDIM / 2) % GDIM);
;           EpiRes E{X + (size_t)gbs * D}; pg8::gemm_phase<EpiRes, pg8::StaticOrder, true, true>(TIDV, lds, gm, S, E); }
;         if (g < NGROUP - 1) { const int g2 = g + 1, gr2 = grows(g2), gbs2 = gbase(g2);
;           pg8::Gemm gm{XN + (size_t)gbs2 * D, wl + WL_WIN, gr2, NIN, D}; pg8::StaticOrder S; S.init(gr2, NIN, GDIM, BIDX);
;           EpiIn E{gb, (const float*)(P.ws + WS_ROT), g2}; pg8::gemm_phase<EpiIn, pg8::StaticOrder, true, true>(TIDV, lds, gm, S, E); }
.Lk7_entry:
	s_mov_b32 s98, 0
	s_cmp_lg_u32 s92, 0x100
	s_cbranch_scc1 .Lk7_mode_done
	s_add_i32 s99, s34, -1
	s_cmp_gt_u32 s99, 1
	s_cbranch_scc1 .Lk7_mode_done
	s_mov_b32 s98, 1
	s_cmp_eq_u32 s31, 6
	s_cbranch_scc0 .Lk7_mode_done
	s_mov_b32 s98, 2
.Lk7_mode_done:
	s_load_dwordx4 s[4:7], s[18:19], 0xe8
	s_mul_i32 s1, s96, 0x2400000
	s_mul_hi_i32 s0, s96, 0x2400000
	s_waitcnt vmcnt(0)
	v_mov_b32_e32 v0, v228
	s_waitcnt lgkmcnt(0)
	s_add_u32 s1, s6, s1
	s_addc_u32 s0, s7, s0
	s_add_u32 s35, s1, 0xc480000
	s_addc_u32 s74, s0, 0
	s_cmp_eq_u32 s34, 0
	s_cselect_b64 s[38:39], -1, 0
	s_and_b64 s[0:1], s[38:39], exec
	v_mov_b32_e32 v0, v228
	s_mov_b32 s10, s92
	s_mov_b32 s1, s92
	s_mov_b32 s2, s82
	s_mov_b32 s3, s92
	s_cselect_b32 s0, 35, 32
	s_abs_i32 s10, s10
	v_cvt_f32_u32_e32 v0, s10
	s_lshr_b32 s11, s3, 31
	s_add_i32 s3, s3, s11
	s_sub_i32 s11, 0, s10
	v_rcp_iflag_f32_e32 v0, v0
	s_ashr_i32 s3, s3, 1
	s_add_i32 s3, s3, s2
	s_ashr_i32 s2, s3, 31
	v_mul_f32_e32 v0, 0x4f7ffffe, v0
	v_cvt_u32_f32_e32 v0, v0
	s_abs_i32 s3, s3
	v_writelane_b32 v254, s68, 24
	v_mov_b32_e32 v14, v228
	v_readfirstlane_b32 s12, v0
	s_mul_i32 s11, s11, s12
	s_mul_hi_u32 s11, s12, s11
	s_add_i32 s12, s12, s11
	s_mul_hi_u32 s11, s3, s12
	s_mul_i32 s11, s11, s10
	s_sub_i32 s3, s3, s11
	s_sub_i32 s11, s3, s10
	s_cmp_ge_u32 s3, s10
	s_cselect_b32 s3, s11, s3
	s_sub_i32 s11, s3, s10
	s_cmp_ge_u32 s3, s10
	s_cselect_b32 s3, s11, s3
	s_xor_b32 s3, s3, s2
	s_sub_i32 s2, s3, s2
	s_lshl_b32 s12, s0, 2
	v_writelane_b32 v254, s69, 25
	s_cmp_ge_i32 s2, s12
	v_readfirstlane_b32 s33, v14
	s_cbranch_scc1 .LBB0_227
	s_cmp_eq_u32 s98, 2
	s_cbranch_scc1 .LBB0_227
	s_ashr_i32 s11, s2, 31
	s_lshr_b32 s16, s11, 29
	s_add_i32 s36, s2, s16
	s_lshr_b32 s3, s0, 1
	s_and_b32 s16, s36, -8
	s_mov_b64 s[94:95], s[18:19]
	s_and_b32 s10, s12, 4
	s_sub_i32 s21, s2, s16
	s_add_i32 s18, s3, 1
	s_cmp_ge_i32 s21, s10
	s_mov_b64 s[16:17], -1
	s_mul_i32 s19, s18, s10
	s_cbranch_scc0 .LBB0_206
	s_sub_i32 s16, s21, s10
	s_mul_i32 s16, s16, s3
	s_add_i32 s20, s16, s19
	s_mov_b64 s[16:17], 0

;     DI bool next(int i, Unit& u) const { if (!S.next(i / 3, u)) return false; const int z = i % 3; u.z = z; u.offA = (unsigned)z * (unsigned)(G0ROWS * 512 * 2); u.offB = (unsigned)z * (unsigned)(524288 * 2); return true; }
;     DI bool next(int i, Unit& u) const { const int j = i * G + c; if (j >= 3 * 4 * NKSL) return false; u.pm = MMAIN / 256 + j / (4 * NKSL); u.pn = (j / NKSL) & 3; const int kh = j % NKSL; u.z = kh; u.offA = (unsigned)(kh * 512); u.offB = (unsigned)(kh * 512); return true; }
;     __host__ __device__ bool next(int i, Unit& u) const {
;         const long L = (long)i * G + c; if (L >= nwg) return false;
;         int wgid = (int)L; { const int q = nwg / NXCD, r = nwg % NXCD, xcd = wgid % NXCD, off = wgid / NXCD; wgid = (xcd < r ? xcd * (q + 1) : r * (q + 1) + (xcd - r) * q) + off; }
;         const int nig = WGM * nN, gid = wgid / nig, fm = gid * WGM, gsz = (nM - fm) < WGM ? (nM - fm) : WGM;
;         u.pm = fm + ((wgid % nig) % gsz); u.pn = (wgid % nig) / gsz; return true;
.LBB0_234:
	s_cmp_eq_u32 s98, 0
	s_cbranch_scc1 .Lgi_a_done
	s_cmp_eq_u32 s98, 2
	s_cbranch_scc1 .Lgi_a_early
	s_mov_b32 s2, s79
	s_cmp_lt_u32 s2, 0x280
	s_cselect_b64 s[16:17], -1, 0
	s_and_b32 s3, s2, 7
	s_lshr_b32 s2, s2, 3
	s_lshr_b32 s5, s3, 1
	s_lshl_b32 s5, s5, 3
	s_and_b32 s10, s2, 7
	s_add_i32 s4, s5, s10
	s_and_b32 s3, s3, 1
	s_mul_i32 s3, s3, 10
	s_lshr_b32 s2, s2, 3
	s_add_i32 s40, s3, s2
	s_cmp_lt_u32 s40, 6
	s_cbranch_scc1 .Lgi_a_done
	s_add_i32 s40, s40, 8
	s_branch .Lgi_a_done
.Lgi_a_early:
	s_add_i32 s2, s79, 0xffffff80
	s_cmp_lt_u32 s2, 0x100
	s_cselect_b64 s[16:17], -1, 0
	s_and_b32 s3, s2, 7
	s_lshr_b32 s2, s2, 3
	s_lshl_b32 s3, s3, 2
	s_and_b32 s5, s2, 3
	s_add_i32 s4, s3, s5
	s_lshr_b32 s2, s2, 2
	s_add_i32 s40, s2, 6

;     DI bool next(int i, Unit& u) const { if (!S.next(i / 3, u)) return false; const int z = i % 3; u.z = z; u.offA = (unsigned)z * (unsigned)(G0ROWS * 512 * 2); u.offB = (unsigned)z * (unsigned)(524288 * 2); return true; }
;     DI bool next(int i, Unit& u) const { const int j = i * G + c; if (j >= 3 * 4 * NKSL) return false; u.pm = MMAIN / 256 + j / (4 * NKSL); u.pn = (j / NKSL) & 3; const int kh = j % NKSL; u.z = kh; u.offA = (unsigned)(kh * 512); u.offB = (unsigned)(kh * 512); return true; }
;     __host__ __device__ bool next(int i, Unit& u) const {
;         const long L = (long)i * G + c; if (L >= nwg) return false;
;         int wgid = (int)L; { const int q = nwg / NXCD, r = nwg % NXCD, xcd = wgid % NXCD, off = wgid / NXCD; wgid = (xcd < r ? xcd * (q + 1) : r * (q + 1) + (xcd - r) * q) + off; }
;         const int nig = WGM * nN, gid = wgid / nig, fm = gid * WGM, gsz = (nM - fm) < WGM ? (nM - fm) : WGM;
;         u.pm = fm + ((wgid % nig) % gsz); u.pn = (wgid % nig) / gsz; return true;
.LBB0_240:
	s_add_i32 s36, s36, 1
	s_cmp_eq_u32 s98, 0
	s_cbranch_scc1 .Lgi_b_orig
	s_cmp_eq_u32 s98, 2
	s_cbranch_scc1 .Lgi_b_early
	s_mul_i32 s0, s36, s78
	s_add_i32 s0, s0, s79
	s_cmp_lt_u32 s0, 0x280
	s_cselect_b64 s[38:39], -1, 0
	s_cbranch_scc0 .Lgi_b_done
	s_and_b32 s1, s0, 7
	s_lshr_b32 s0, s0, 3
	s_lshr_b32 s2, s1, 1
	s_lshl_b32 s2, s2, 3
	s_and_b32 s3, s0, 7
	s_add_i32 s56, s2, s3
	s_and_b32 s1, s1, 1
	s_mul_i32 s1, s1, 10
	s_lshr_b32 s0, s0, 3
	s_add_i32 s54, s1, s0
	s_cmp_lt_u32 s54, 6
	s_cbranch_scc1 .Lgi_b_done
	s_add_i32 s54, s54, 8
	s_branch .Lgi_b_done
.Lgi_b_early:
	s_add_i32 s0, s78, 0xffffff80
	s_mul_i32 s0, s0, s36
	s_add_i32 s0, s0, s79
	s_add_i32 s0, s0, 0xffffff80
	s_cmp_lt_u32 s0, 0x100
	s_cselect_b64 s[38:39], -1, 0
	s_cbranch_scc0 .Lgi_b_done
	s_and_b32 s1, s0, 7
	s_lshr_b32 s0, s0, 3
	s_lshl_b32 s1, s1, 2
	s_and_b32 s2, s0, 3
	s_add_i32 s56, s1, s2
	s_lshr_b32 s0, s0, 2
	s_add_i32 s54, s0, 6
.Lgi_b_done:
	s_not_b64 vcc, s[38:39]
	s_branch .LBB0_246
.Lgi_b_orig:
	s_mul_i32 s0, s36, s37
	s_mul_hi_u32 s1, s36, s78
	s_add_i32 s1, s1, s0
	s_mul_i32 s0, s36, s78
	s_add_u32 s6, s0, s79
	s_addc_u32 s7, s1, s10
	v_mov_b64_e32 v[0:1], s[46:47]
	v_cmp_ge_i64_e32 vcc, s[6:7], v[0:1]
	v_cmp_lt_i64_e64 s[38:39], s[6:7], v[0:1]
	s_cbranch_vccnz .LBB0_246
	s_ashr_i32 s0, s6, 31
	s_lshr_b32 s0, s0, 29
	s_add_i32 s0, s6, s0
	s_and_b32 s1, s0, -8
	s_sub_i32 s1, s6, s1
	s_cmp_ge_i32 s1, s18
	s_mov_b64 s[6:7], -1
	s_cbranch_scc0 .LBB0_243
	s_sub_i32 s2, s1, s18
	s_mul_i32 s2, s2, s72
	s_mul_i32 s3, s19, s18
	s_add_i32 s2, s2, s3
	s_mov_b64 s[6:7], 0

; #define TIDV tid_opaque()
; #define BIDX bid_opaque()
; #define GDIM gdim_opaque()
; template <int KIND> DI void run_phase(PARAMS P, int l, int g) {
;     ...
;     else if constexpr (KIND == 6) {
;         pg8::Gemm gm{(const bf16_t*)((unsigned char*)P.out + DS_OB), wl + WL_WBR, gr, D, 512};
;         BrOrder S; S.S.init(gr, D, GDIM, BIDX);
;         EpiBr E{gb + (size_t)CP_ZG * G0ROWS, (float*)((unsigned char*)P.out + DS_MIXF), (bf16_t*)((unsigned char*)P.out + DS_MIXB)};
;         pg8::gemm_phase<EpiBr, BrOrder, true, true>(TIDV, lds, gm, S, E); }
.LBB0_395:
	s_and_b64 vcc, exec, s[4:5]
	s_cbranch_vccz .LBB0_456
	s_cmp_lg_u32 s92, 0x100
	s_cbranch_scc1 .Lk6_normal
	s_add_i32 s99, s34, -1
	s_cmp_gt_u32 s99, 1
	s_cbranch_scc1 .Lk6_normal
	s_cmp_lt_u32 s82, 0x80
	s_cbranch_scc1 .Lk6_normal
	s_branch .Lk7_entry
.Lk6_normal:
	s_waitcnt vmcnt(0)
	v_mov_b32_e32 v0, v228
	s_cmp_eq_u32 s34, 0
	s_cselect_b32 s0, 35, 32
	v_mov_b32_e32 v0, v228
	s_mov_b32 s1, s92
	s_mov_b32 s2, s82
	s_lshl_b32 s12, s0, 2
	v_mov_b32_e32 v8, v228
	s_cmp_lt_i32 s2, s12
	s_cselect_b64 s[16:17], -1, 0
	s_cmp_ge_i32 s2, s12
	v_readfirstlane_b32 s33, v8
	s_cbranch_scc1 .LBB0_402
	s_ashr_i32 s3, s2, 31
	s_lshr_b32 s3, s3, 29
	s_add_i32 s3, s2, s3
	s_lshr_b32 s11, s0, 1
	s_and_b32 s4, s3, -8
	s_mov_b64 s[20:21], s[18:19]
	s_and_b32 s18, s12, 4
	s_sub_i32 s6, s2, s4
	s_add_i32 s7, s11, 1
	s_cmp_ge_i32 s6, s18
	s_mov_b64 s[4:5], -1
	s_cbranch_scc0 .LBB0_399
	s_sub_i32 s5, s6, s18
	s_mul_i32 s4, s7, s18
	s_mul_i32 s5, s5, s11
	s_add_i32 s10, s5, s4
	s_mov_b64 s[4:5], 0
